# P0 weight transposes batched: 7 tiles fetched at once per workgroup (2 exposed round trips and 4 barriers instead of 13-14 and 27)
# speedup vs baseline: 1.0000x; 1.0000x over previous
.LBB0_28:
	v_and_b32_e32 v0, 63, v208
	v_lshrrev_b32_e32 v1, 6, v208
	v_lshlrev_b32_e32 v2, 2, v0
	v_mul_u32_u24_e32 v3, 0x41, v1
	v_add_u32_e32 v3, v3, v0
	v_lshlrev_b32_e32 v3, 2, v3
	v_lshrrev_b32_e32 v4, 3, v208
	v_and_b32_e32 v5, 7, v208
	v_lshlrev_b32_e32 v5, 3, v5
	v_mul_u32_u24_e32 v6, 0x41, v5
	v_add_u32_e32 v6, v6, v4
	v_lshlrev_b32_e32 v6, 2, v6
	v_lshlrev_b32_e32 v7, 1, v5
	s_mov_b32 s0, s20
.Lp0t_batch:
	s_cmpk_gt_i32 s0, 0xd7f
	s_cbranch_scc1 .LBB0_43
	s_mov_b32 s1, s0
	s_cmpk_lt_u32 s1, 0x580
	s_cbranch_scc0 .Lp0t_ld_1_n0
	s_mov_b32 s2, s1
	s_mul_hi_u32 s3, s2, 0x2e8ba2e9
	s_lshr_b32 s3, s3, 4
	s_mul_i32 s4, s3, 88
	s_sub_u32 s4, s2, s4
	s_mul_i32 s5, s3, 0x160000
	s_lshl_b32 s6, s4, 8
	s_add_u32 s5, s5, s6
	s_add_u32 s10, s68, s5
	s_addc_u32 s11, s69, 0
	s_mov_b32 s12, 0x5800
	s_branch .Lp0t_ld_1_done
.Lp0t_ld_1_n0:
	s_cmpk_lt_u32 s1, 0x780
	s_cbranch_scc0 .Lp0t_ld_1_n1
	s_sub_u32 s2, s1, 0x580
	s_lshr_b32 s3, s2, 4
	s_and_b32 s4, s2, 15
	s_mul_i32 s5, s3, 0x40000
	s_lshl_b32 s6, s4, 8
	s_add_u32 s5, s5, s6
	s_add_u32 s10, s82, s5
	s_addc_u32 s11, s83, 0
	s_mov_b32 s12, 0x1000
	s_branch .Lp0t_ld_1_done
.Lp0t_ld_1_n1:
	s_cmpk_lt_u32 s1, 0xb80
	s_cbranch_scc0 .Lp0t_ld_1_n2
	s_sub_u32 s2, s1, 0x780
	s_lshr_b32 s3, s2, 6
	s_and_b32 s4, s2, 63
	s_mul_i32 s5, s3, 0x100000
	s_lshl_b32 s6, s4, 8
	s_add_u32 s5, s5, s6
	s_add_u32 s10, s84, s5
	s_addc_u32 s11, s85, 0
	s_mov_b32 s12, 0x4000
	s_branch .Lp0t_ld_1_done
.Lp0t_ld_1_n2:
	s_sub_u32 s2, s1, 0xb80
	s_lshr_b32 s3, s2, 4
	s_and_b32 s4, s2, 15
	s_mul_i32 s5, s3, 0x40000
	s_lshl_b32 s6, s4, 8
	s_add_u32 s5, s5, s6
	s_add_u32 s10, s86, s5
	s_addc_u32 s11, s87, 0
	s_mov_b32 s12, 0x1000
.Lp0t_ld_1_done:
	v_mad_u32_u24 v8, v1, s12, v2
	s_lshl_b32 s13, s12, 3
	global_load_dword v126, v8, s[10:11]
	s_add_u32 s10, s10, s13
	s_addc_u32 s11, s11, 0
	global_load_dword v127, v8, s[10:11]
	s_add_u32 s10, s10, s13
	s_addc_u32 s11, s11, 0
	global_load_dword v128, v8, s[10:11]
	s_add_u32 s10, s10, s13
	s_addc_u32 s11, s11, 0
	global_load_dword v129, v8, s[10:11]
	s_add_u32 s10, s10, s13
	s_addc_u32 s11, s11, 0
	global_load_dword v130, v8, s[10:11]
	s_add_u32 s10, s10, s13
	s_addc_u32 s11, s11, 0
	global_load_dword v131, v8, s[10:11]
	s_add_u32 s10, s10, s13
	s_addc_u32 s11, s11, 0
	global_load_dword v132, v8, s[10:11]
	s_add_u32 s10, s10, s13
	s_addc_u32 s11, s11, 0
	global_load_dword v133, v8, s[10:11]
	s_mul_i32 s1, s48, 1
	s_add_u32 s1, s0, s1
	s_cmpk_gt_i32 s1, 0xd7f
	s_cbranch_scc1 .Lp0t_ld_end
	s_cmpk_lt_u32 s1, 0x580
	s_cbranch_scc0 .Lp0t_ld_2_n0
	s_mov_b32 s2, s1
	s_mul_hi_u32 s3, s2, 0x2e8ba2e9
	s_lshr_b32 s3, s3, 4
	s_mul_i32 s4, s3, 88
	s_sub_u32 s4, s2, s4
	s_mul_i32 s5, s3, 0x160000
	s_lshl_b32 s6, s4, 8
	s_add_u32 s5, s5, s6
	s_add_u32 s10, s68, s5
	s_addc_u32 s11, s69, 0
	s_mov_b32 s12, 0x5800
	s_branch .Lp0t_ld_2_done

.Lp0t_ld_2_done:
	v_mad_u32_u24 v8, v1, s12, v2
	s_lshl_b32 s13, s12, 3
	global_load_dword v134, v8, s[10:11]
	s_add_u32 s10, s10, s13
	s_addc_u32 s11, s11, 0
	global_load_dword v135, v8, s[10:11]
	s_add_u32 s10, s10, s13
	s_addc_u32 s11, s11, 0
	global_load_dword v136, v8, s[10:11]
	s_add_u32 s10, s10, s13
	s_addc_u32 s11, s11, 0
	global_load_dword v137, v8, s[10:11]
	s_add_u32 s10, s10, s13
	s_addc_u32 s11, s11, 0
	global_load_dword v138, v8, s[10:11]
	s_add_u32 s10, s10, s13
	s_addc_u32 s11, s11, 0
	global_load_dword v139, v8, s[10:11]
	s_add_u32 s10, s10, s13
	s_addc_u32 s11, s11, 0
	global_load_dword v140, v8, s[10:11]
	s_add_u32 s10, s10, s13
	s_addc_u32 s11, s11, 0
	global_load_dword v141, v8, s[10:11]
	s_mul_i32 s1, s48, 2
	s_add_u32 s1, s0, s1
	s_cmpk_gt_i32 s1, 0xd7f
	s_cbranch_scc1 .Lp0t_ld_end
	s_cmpk_lt_u32 s1, 0x580
	s_cbranch_scc0 .Lp0t_ld_3_n0
	s_mov_b32 s2, s1
	s_mul_hi_u32 s3, s2, 0x2e8ba2e9
	s_lshr_b32 s3, s3, 4
	s_mul_i32 s4, s3, 88
	s_sub_u32 s4, s2, s4
	s_mul_i32 s5, s3, 0x160000
	s_lshl_b32 s6, s4, 8
	s_add_u32 s5, s5, s6
	s_add_u32 s10, s68, s5
	s_addc_u32 s11, s69, 0
	s_mov_b32 s12, 0x5800
	s_branch .Lp0t_ld_3_done

.Lp0t_ld_3_done:
	v_mad_u32_u24 v8, v1, s12, v2
	s_lshl_b32 s13, s12, 3
	global_load_dword v142, v8, s[10:11]
	s_add_u32 s10, s10, s13
	s_addc_u32 s11, s11, 0
	global_load_dword v143, v8, s[10:11]
	s_add_u32 s10, s10, s13
	s_addc_u32 s11, s11, 0
	global_load_dword v144, v8, s[10:11]
	s_add_u32 s10, s10, s13
	s_addc_u32 s11, s11, 0
	global_load_dword v145, v8, s[10:11]
	s_add_u32 s10, s10, s13
	s_addc_u32 s11, s11, 0
	global_load_dword v146, v8, s[10:11]
	s_add_u32 s10, s10, s13
	s_addc_u32 s11, s11, 0
	global_load_dword v147, v8, s[10:11]
	s_add_u32 s10, s10, s13
	s_addc_u32 s11, s11, 0
	global_load_dword v148, v8, s[10:11]
	s_add_u32 s10, s10, s13
	s_addc_u32 s11, s11, 0
	global_load_dword v149, v8, s[10:11]
	s_mul_i32 s1, s48, 3
	s_add_u32 s1, s0, s1
	s_cmpk_gt_i32 s1, 0xd7f
	s_cbranch_scc1 .Lp0t_ld_end
	s_cmpk_lt_u32 s1, 0x580
	s_cbranch_scc0 .Lp0t_ld_4_n0
	s_mov_b32 s2, s1
	s_mul_hi_u32 s3, s2, 0x2e8ba2e9
	s_lshr_b32 s3, s3, 4
	s_mul_i32 s4, s3, 88
	s_sub_u32 s4, s2, s4
	s_mul_i32 s5, s3, 0x160000
	s_lshl_b32 s6, s4, 8
	s_add_u32 s5, s5, s6
	s_add_u32 s10, s68, s5
	s_addc_u32 s11, s69, 0
	s_mov_b32 s12, 0x5800
	s_branch .Lp0t_ld_4_done

.Lp0t_ld_4_done:
	v_mad_u32_u24 v8, v1, s12, v2
	s_lshl_b32 s13, s12, 3
	global_load_dword v150, v8, s[10:11]
	s_add_u32 s10, s10, s13
	s_addc_u32 s11, s11, 0
	global_load_dword v151, v8, s[10:11]
	s_add_u32 s10, s10, s13
	s_addc_u32 s11, s11, 0
	global_load_dword v152, v8, s[10:11]
	s_add_u32 s10, s10, s13
	s_addc_u32 s11, s11, 0
	global_load_dword v153, v8, s[10:11]
	s_add_u32 s10, s10, s13
	s_addc_u32 s11, s11, 0
	global_load_dword v154, v8, s[10:11]
	s_add_u32 s10, s10, s13
	s_addc_u32 s11, s11, 0
	global_load_dword v155, v8, s[10:11]
	s_add_u32 s10, s10, s13
	s_addc_u32 s11, s11, 0
	global_load_dword v156, v8, s[10:11]
	s_add_u32 s10, s10, s13
	s_addc_u32 s11, s11, 0
	global_load_dword v157, v8, s[10:11]
	s_mul_i32 s1, s48, 4
	s_add_u32 s1, s0, s1
	s_cmpk_gt_i32 s1, 0xd7f
	s_cbranch_scc1 .Lp0t_ld_end
	s_cmpk_lt_u32 s1, 0x580
	s_cbranch_scc0 .Lp0t_ld_5_n0
	s_mov_b32 s2, s1
	s_mul_hi_u32 s3, s2, 0x2e8ba2e9
	s_lshr_b32 s3, s3, 4
	s_mul_i32 s4, s3, 88
	s_sub_u32 s4, s2, s4
	s_mul_i32 s5, s3, 0x160000
	s_lshl_b32 s6, s4, 8
	s_add_u32 s5, s5, s6
	s_add_u32 s10, s68, s5
	s_addc_u32 s11, s69, 0
	s_mov_b32 s12, 0x5800
	s_branch .Lp0t_ld_5_done

.Lp0t_ld_5_done:
	v_mad_u32_u24 v8, v1, s12, v2
	s_lshl_b32 s13, s12, 3
	global_load_dword v158, v8, s[10:11]
	s_add_u32 s10, s10, s13
	s_addc_u32 s11, s11, 0
	global_load_dword v159, v8, s[10:11]
	s_add_u32 s10, s10, s13
	s_addc_u32 s11, s11, 0
	global_load_dword v160, v8, s[10:11]
	s_add_u32 s10, s10, s13
	s_addc_u32 s11, s11, 0
	global_load_dword v161, v8, s[10:11]
	s_add_u32 s10, s10, s13
	s_addc_u32 s11, s11, 0
	global_load_dword v162, v8, s[10:11]
	s_add_u32 s10, s10, s13
	s_addc_u32 s11, s11, 0
	global_load_dword v163, v8, s[10:11]
	s_add_u32 s10, s10, s13
	s_addc_u32 s11, s11, 0
	global_load_dword v164, v8, s[10:11]
	s_add_u32 s10, s10, s13
	s_addc_u32 s11, s11, 0
	global_load_dword v165, v8, s[10:11]
	s_mul_i32 s1, s48, 5
	s_add_u32 s1, s0, s1
	s_cmpk_gt_i32 s1, 0xd7f
	s_cbranch_scc1 .Lp0t_ld_end
	s_cmpk_lt_u32 s1, 0x580
	s_cbranch_scc0 .Lp0t_ld_6_n0
	s_mov_b32 s2, s1
	s_mul_hi_u32 s3, s2, 0x2e8ba2e9
	s_lshr_b32 s3, s3, 4
	s_mul_i32 s4, s3, 88
	s_sub_u32 s4, s2, s4
	s_mul_i32 s5, s3, 0x160000
	s_lshl_b32 s6, s4, 8
	s_add_u32 s5, s5, s6
	s_add_u32 s10, s68, s5
	s_addc_u32 s11, s69, 0
	s_mov_b32 s12, 0x5800
	s_branch .Lp0t_ld_6_done

.Lp0t_ld_6_done:
	v_mad_u32_u24 v8, v1, s12, v2
	s_lshl_b32 s13, s12, 3
	global_load_dword v166, v8, s[10:11]
	s_add_u32 s10, s10, s13
	s_addc_u32 s11, s11, 0
	global_load_dword v167, v8, s[10:11]
	s_add_u32 s10, s10, s13
	s_addc_u32 s11, s11, 0
	global_load_dword v168, v8, s[10:11]
	s_add_u32 s10, s10, s13
	s_addc_u32 s11, s11, 0
	global_load_dword v169, v8, s[10:11]
	s_add_u32 s10, s10, s13
	s_addc_u32 s11, s11, 0
	global_load_dword v170, v8, s[10:11]
	s_add_u32 s10, s10, s13
	s_addc_u32 s11, s11, 0
	global_load_dword v171, v8, s[10:11]
	s_add_u32 s10, s10, s13
	s_addc_u32 s11, s11, 0
	global_load_dword v172, v8, s[10:11]
	s_add_u32 s10, s10, s13
	s_addc_u32 s11, s11, 0
	global_load_dword v173, v8, s[10:11]
	s_mul_i32 s1, s48, 6
	s_add_u32 s1, s0, s1
	s_cmpk_gt_i32 s1, 0xd7f
	s_cbranch_scc1 .Lp0t_ld_end
	s_cmpk_lt_u32 s1, 0x580
	s_cbranch_scc0 .Lp0t_ld_7_n0
	s_mov_b32 s2, s1
	s_mul_hi_u32 s3, s2, 0x2e8ba2e9
	s_lshr_b32 s3, s3, 4
	s_mul_i32 s4, s3, 88
	s_sub_u32 s4, s2, s4
	s_mul_i32 s5, s3, 0x160000
	s_lshl_b32 s6, s4, 8
	s_add_u32 s5, s5, s6
	s_add_u32 s10, s68, s5
	s_addc_u32 s11, s69, 0
	s_mov_b32 s12, 0x5800
	s_branch .Lp0t_ld_7_done

.Lp0t_ld_7_done:
	v_mad_u32_u24 v8, v1, s12, v2
	s_lshl_b32 s13, s12, 3
	global_load_dword v174, v8, s[10:11]
	s_add_u32 s10, s10, s13
	s_addc_u32 s11, s11, 0
	global_load_dword v175, v8, s[10:11]
	s_add_u32 s10, s10, s13
	s_addc_u32 s11, s11, 0
	global_load_dword v176, v8, s[10:11]
	s_add_u32 s10, s10, s13
	s_addc_u32 s11, s11, 0
	global_load_dword v177, v8, s[10:11]
	s_add_u32 s10, s10, s13
	s_addc_u32 s11, s11, 0
	global_load_dword v178, v8, s[10:11]
	s_add_u32 s10, s10, s13
	s_addc_u32 s11, s11, 0
	global_load_dword v179, v8, s[10:11]
	s_add_u32 s10, s10, s13
	s_addc_u32 s11, s11, 0
	global_load_dword v180, v8, s[10:11]
	s_add_u32 s10, s10, s13
	s_addc_u32 s11, s11, 0
	global_load_dword v181, v8, s[10:11]
.Lp0t_ld_end:
	s_waitcnt vmcnt(0)
	s_mov_b32 s1, s0
	ds_write_b32 v3, v126
	ds_write_b32 v3, v127 offset:2080
	ds_write_b32 v3, v128 offset:4160
	ds_write_b32 v3, v129 offset:6240
	ds_write_b32 v3, v130 offset:8320
	ds_write_b32 v3, v131 offset:10400
	ds_write_b32 v3, v132 offset:12480
	ds_write_b32 v3, v133 offset:14560
	s_mul_i32 s1, s48, 1
	s_add_u32 s1, s0, s1
	s_cmpk_gt_i32 s1, 0xd7f
	s_cbranch_scc1 .Lp0t_wr_end
	v_add_u32_e32 v9, 0x4100, v3
	ds_write_b32 v9, v134
	ds_write_b32 v9, v135 offset:2080
	ds_write_b32 v9, v136 offset:4160
	ds_write_b32 v9, v137 offset:6240
	ds_write_b32 v9, v138 offset:8320
	ds_write_b32 v9, v139 offset:10400
	ds_write_b32 v9, v140 offset:12480
	ds_write_b32 v9, v141 offset:14560
	s_mul_i32 s1, s48, 2
	s_add_u32 s1, s0, s1
	s_cmpk_gt_i32 s1, 0xd7f
	s_cbranch_scc1 .Lp0t_wr_end
	v_add_u32_e32 v9, 0x8200, v3
	ds_write_b32 v9, v142
	ds_write_b32 v9, v143 offset:2080
	ds_write_b32 v9, v144 offset:4160
	ds_write_b32 v9, v145 offset:6240
	ds_write_b32 v9, v146 offset:8320
	ds_write_b32 v9, v147 offset:10400
	ds_write_b32 v9, v148 offset:12480
	ds_write_b32 v9, v149 offset:14560
	s_mul_i32 s1, s48, 3
	s_add_u32 s1, s0, s1
	s_cmpk_gt_i32 s1, 0xd7f
	s_cbranch_scc1 .Lp0t_wr_end
	v_add_u32_e32 v9, 0xc300, v3
	ds_write_b32 v9, v150
	ds_write_b32 v9, v151 offset:2080
	ds_write_b32 v9, v152 offset:4160
	ds_write_b32 v9, v153 offset:6240
	ds_write_b32 v9, v154 offset:8320
	ds_write_b32 v9, v155 offset:10400
	ds_write_b32 v9, v156 offset:12480
	ds_write_b32 v9, v157 offset:14560
	s_mul_i32 s1, s48, 4
	s_add_u32 s1, s0, s1
	s_cmpk_gt_i32 s1, 0xd7f
	s_cbranch_scc1 .Lp0t_wr_end
	v_add_u32_e32 v9, 0x10400, v3
	ds_write_b32 v9, v158
	ds_write_b32 v9, v159 offset:2080
	ds_write_b32 v9, v160 offset:4160
	ds_write_b32 v9, v161 offset:6240
	ds_write_b32 v9, v162 offset:8320
	ds_write_b32 v9, v163 offset:10400
	ds_write_b32 v9, v164 offset:12480
	ds_write_b32 v9, v165 offset:14560
	s_mul_i32 s1, s48, 5
	s_add_u32 s1, s0, s1
	s_cmpk_gt_i32 s1, 0xd7f
	s_cbranch_scc1 .Lp0t_wr_end
	v_add_u32_e32 v9, 0x14500, v3
	ds_write_b32 v9, v166
	ds_write_b32 v9, v167 offset:2080
	ds_write_b32 v9, v168 offset:4160
	ds_write_b32 v9, v169 offset:6240
	ds_write_b32 v9, v170 offset:8320
	ds_write_b32 v9, v171 offset:10400
	ds_write_b32 v9, v172 offset:12480
	ds_write_b32 v9, v173 offset:14560
	s_mul_i32 s1, s48, 6
	s_add_u32 s1, s0, s1
	s_cmpk_gt_i32 s1, 0xd7f
	s_cbranch_scc1 .Lp0t_wr_end
	v_add_u32_e32 v9, 0x18600, v3
	ds_write_b32 v9, v174
	ds_write_b32 v9, v175 offset:2080
	ds_write_b32 v9, v176 offset:4160
	ds_write_b32 v9, v177 offset:6240
	ds_write_b32 v9, v178 offset:8320
	ds_write_b32 v9, v179 offset:10400
	ds_write_b32 v9, v180 offset:12480
	ds_write_b32 v9, v181 offset:14560
.Lp0t_wr_end:
	s_waitcnt lgkmcnt(0)
	s_barrier
	s_mov_b32 s1, s0
	s_cmpk_lt_u32 s1, 0x580
	s_cbranch_scc0 .Lp0t_st_8_n0
	s_mov_b32 s2, s1
	s_mul_hi_u32 s3, s2, 0x2e8ba2e9
	s_lshr_b32 s3, s3, 4
	s_mul_i32 s4, s3, 88
	s_sub_u32 s4, s2, s4
	s_mul_i32 s5, s4, 0x20000
	s_lshl_b32 s6, s3, 7
	s_add_u32 s5, s5, s6
	s_add_u32 s14, s90, s5
	s_addc_u32 s15, s91, 0
	s_mov_b32 s16, 0x800
	s_branch .Lp0t_st_8_done
.Lp0t_st_8_n0:
	s_cmpk_lt_u32 s1, 0x780
	s_cbranch_scc0 .Lp0t_st_8_n1
	s_sub_u32 s2, s1, 0x580
	s_lshr_b32 s3, s2, 4
	s_and_b32 s4, s2, 15
	s_mul_i32 s5, s4, 0x40000
	s_lshl_b32 s6, s3, 7
	s_add_u32 s5, s5, s6
	s_add_u32 s5, s5, 0xb00000
	s_add_u32 s14, s90, s5
	s_addc_u32 s15, s91, 0
	s_mov_b32 s16, 0x1000
	s_branch .Lp0t_st_8_done
.Lp0t_st_8_n1:
	s_cmpk_lt_u32 s1, 0xb80
	s_cbranch_scc0 .Lp0t_st_8_n2
	s_sub_u32 s2, s1, 0x780
	s_lshr_b32 s3, s2, 6
	s_and_b32 s4, s2, 63
	s_mul_i32 s5, s4, 0x20000
	s_lshl_b32 s6, s3, 7
	s_add_u32 s5, s5, s6
	s_add_u32 s5, s5, 0xf00000
	s_add_u32 s14, s90, s5
	s_addc_u32 s15, s91, 0
	s_mov_b32 s16, 0x800
	s_branch .Lp0t_st_8_done
.Lp0t_st_8_n2:
	s_sub_u32 s2, s1, 0xb80
	s_lshr_b32 s3, s2, 4
	s_and_b32 s4, s2, 15
	s_mul_i32 s5, s4, 0x40000
	s_lshl_b32 s6, s3, 7
	s_add_u32 s5, s5, s6
	s_add_u32 s5, s5, 0x1700000
	s_add_u32 s14, s90, s5
	s_addc_u32 s15, s91, 0
	s_mov_b32 s16, 0x1000
.Lp0t_st_8_done:
	v_add_u32_e32 v9, 0x0, v6
	v_add_u32_e32 v12, 0x400, v9
	ds_read2_b32 v[14:15], v9 offset1:65
	ds_read2_b32 v[16:17], v9 offset0:130 offset1:195
	ds_read2_b32 v[18:19], v12 offset0:4 offset1:69
	ds_read2_b32 v[20:21], v12 offset0:134 offset1:199
	v_mad_u32_u24 v13, v4, s16, v7
	s_waitcnt lgkmcnt(0)
	v_cvt_pk_bf16_f32 v22, v14, v15
	v_cvt_pk_bf16_f32 v23, v16, v17
	v_cvt_pk_bf16_f32 v24, v18, v19
	v_cvt_pk_bf16_f32 v25, v20, v21
	global_store_dwordx4 v13, v[22:25], s[14:15]
	s_mul_i32 s1, s48, 1
	s_add_u32 s1, s0, s1
	s_cmpk_gt_i32 s1, 0xd7f
	s_cbranch_scc1 .Lp0t_st_end
	s_cmpk_lt_u32 s1, 0x580
	s_cbranch_scc0 .Lp0t_st_9_n0
	s_mov_b32 s2, s1
	s_mul_hi_u32 s3, s2, 0x2e8ba2e9
	s_lshr_b32 s3, s3, 4
	s_mul_i32 s4, s3, 88
	s_sub_u32 s4, s2, s4
	s_mul_i32 s5, s4, 0x20000
	s_lshl_b32 s6, s3, 7
	s_add_u32 s5, s5, s6
	s_add_u32 s14, s90, s5
	s_addc_u32 s15, s91, 0
	s_mov_b32 s16, 0x800
	s_branch .Lp0t_st_9_done

.Lp0t_st_9_done:
	v_add_u32_e32 v9, 0x4100, v6
	v_add_u32_e32 v12, 0x400, v9
	ds_read2_b32 v[14:15], v9 offset1:65
	ds_read2_b32 v[16:17], v9 offset0:130 offset1:195
	ds_read2_b32 v[18:19], v12 offset0:4 offset1:69
	ds_read2_b32 v[20:21], v12 offset0:134 offset1:199
	v_mad_u32_u24 v13, v4, s16, v7
	s_waitcnt lgkmcnt(0)
	v_cvt_pk_bf16_f32 v22, v14, v15
	v_cvt_pk_bf16_f32 v23, v16, v17
	v_cvt_pk_bf16_f32 v24, v18, v19
	v_cvt_pk_bf16_f32 v25, v20, v21
	global_store_dwordx4 v13, v[22:25], s[14:15]
	s_mul_i32 s1, s48, 2
	s_add_u32 s1, s0, s1
	s_cmpk_gt_i32 s1, 0xd7f
	s_cbranch_scc1 .Lp0t_st_end
	s_cmpk_lt_u32 s1, 0x580
	s_cbranch_scc0 .Lp0t_st_10_n0
	s_mov_b32 s2, s1
	s_mul_hi_u32 s3, s2, 0x2e8ba2e9
	s_lshr_b32 s3, s3, 4
	s_mul_i32 s4, s3, 88
	s_sub_u32 s4, s2, s4
	s_mul_i32 s5, s4, 0x20000
	s_lshl_b32 s6, s3, 7
	s_add_u32 s5, s5, s6
	s_add_u32 s14, s90, s5
	s_addc_u32 s15, s91, 0
	s_mov_b32 s16, 0x800
	s_branch .Lp0t_st_10_done

.Lp0t_st_10_done:
	v_add_u32_e32 v9, 0x8200, v6
	v_add_u32_e32 v12, 0x400, v9
	ds_read2_b32 v[14:15], v9 offset1:65
	ds_read2_b32 v[16:17], v9 offset0:130 offset1:195
	ds_read2_b32 v[18:19], v12 offset0:4 offset1:69
	ds_read2_b32 v[20:21], v12 offset0:134 offset1:199
	v_mad_u32_u24 v13, v4, s16, v7
	s_waitcnt lgkmcnt(0)
	v_cvt_pk_bf16_f32 v22, v14, v15
	v_cvt_pk_bf16_f32 v23, v16, v17
	v_cvt_pk_bf16_f32 v24, v18, v19
	v_cvt_pk_bf16_f32 v25, v20, v21
	global_store_dwordx4 v13, v[22:25], s[14:15]
	s_mul_i32 s1, s48, 3
	s_add_u32 s1, s0, s1
	s_cmpk_gt_i32 s1, 0xd7f
	s_cbranch_scc1 .Lp0t_st_end
	s_cmpk_lt_u32 s1, 0x580
	s_cbranch_scc0 .Lp0t_st_11_n0
	s_mov_b32 s2, s1
	s_mul_hi_u32 s3, s2, 0x2e8ba2e9
	s_lshr_b32 s3, s3, 4
	s_mul_i32 s4, s3, 88
	s_sub_u32 s4, s2, s4
	s_mul_i32 s5, s4, 0x20000
	s_lshl_b32 s6, s3, 7
	s_add_u32 s5, s5, s6
	s_add_u32 s14, s90, s5
	s_addc_u32 s15, s91, 0
	s_mov_b32 s16, 0x800
	s_branch .Lp0t_st_11_done

.Lp0t_st_11_done:
	v_add_u32_e32 v9, 0xc300, v6
	v_add_u32_e32 v12, 0x400, v9
	ds_read2_b32 v[14:15], v9 offset1:65
	ds_read2_b32 v[16:17], v9 offset0:130 offset1:195
	ds_read2_b32 v[18:19], v12 offset0:4 offset1:69
	ds_read2_b32 v[20:21], v12 offset0:134 offset1:199
	v_mad_u32_u24 v13, v4, s16, v7
	s_waitcnt lgkmcnt(0)
	v_cvt_pk_bf16_f32 v22, v14, v15
	v_cvt_pk_bf16_f32 v23, v16, v17
	v_cvt_pk_bf16_f32 v24, v18, v19
	v_cvt_pk_bf16_f32 v25, v20, v21
	global_store_dwordx4 v13, v[22:25], s[14:15]
	s_mul_i32 s1, s48, 4
	s_add_u32 s1, s0, s1
	s_cmpk_gt_i32 s1, 0xd7f
	s_cbranch_scc1 .Lp0t_st_end
	s_cmpk_lt_u32 s1, 0x580
	s_cbranch_scc0 .Lp0t_st_12_n0
	s_mov_b32 s2, s1
	s_mul_hi_u32 s3, s2, 0x2e8ba2e9
	s_lshr_b32 s3, s3, 4
	s_mul_i32 s4, s3, 88
	s_sub_u32 s4, s2, s4
	s_mul_i32 s5, s4, 0x20000
	s_lshl_b32 s6, s3, 7
	s_add_u32 s5, s5, s6
	s_add_u32 s14, s90, s5
	s_addc_u32 s15, s91, 0
	s_mov_b32 s16, 0x800
	s_branch .Lp0t_st_12_done

.Lp0t_st_12_done:
	v_add_u32_e32 v9, 0x10400, v6
	v_add_u32_e32 v12, 0x400, v9
	ds_read2_b32 v[14:15], v9 offset1:65
	ds_read2_b32 v[16:17], v9 offset0:130 offset1:195
	ds_read2_b32 v[18:19], v12 offset0:4 offset1:69
	ds_read2_b32 v[20:21], v12 offset0:134 offset1:199
	v_mad_u32_u24 v13, v4, s16, v7
	s_waitcnt lgkmcnt(0)
	v_cvt_pk_bf16_f32 v22, v14, v15
	v_cvt_pk_bf16_f32 v23, v16, v17
	v_cvt_pk_bf16_f32 v24, v18, v19
	v_cvt_pk_bf16_f32 v25, v20, v21
	global_store_dwordx4 v13, v[22:25], s[14:15]
	s_mul_i32 s1, s48, 5
	s_add_u32 s1, s0, s1
	s_cmpk_gt_i32 s1, 0xd7f
	s_cbranch_scc1 .Lp0t_st_end
	s_cmpk_lt_u32 s1, 0x580
	s_cbranch_scc0 .Lp0t_st_13_n0
	s_mov_b32 s2, s1
	s_mul_hi_u32 s3, s2, 0x2e8ba2e9
	s_lshr_b32 s3, s3, 4
	s_mul_i32 s4, s3, 88
	s_sub_u32 s4, s2, s4
	s_mul_i32 s5, s4, 0x20000
	s_lshl_b32 s6, s3, 7
	s_add_u32 s5, s5, s6
	s_add_u32 s14, s90, s5
	s_addc_u32 s15, s91, 0
	s_mov_b32 s16, 0x800
	s_branch .Lp0t_st_13_done

.Lp0t_st_13_done:
	v_add_u32_e32 v9, 0x14500, v6
	v_add_u32_e32 v12, 0x400, v9
	ds_read2_b32 v[14:15], v9 offset1:65
	ds_read2_b32 v[16:17], v9 offset0:130 offset1:195
	ds_read2_b32 v[18:19], v12 offset0:4 offset1:69
	ds_read2_b32 v[20:21], v12 offset0:134 offset1:199
	v_mad_u32_u24 v13, v4, s16, v7
	s_waitcnt lgkmcnt(0)
	v_cvt_pk_bf16_f32 v22, v14, v15
	v_cvt_pk_bf16_f32 v23, v16, v17
	v_cvt_pk_bf16_f32 v24, v18, v19
	v_cvt_pk_bf16_f32 v25, v20, v21
	global_store_dwordx4 v13, v[22:25], s[14:15]
	s_mul_i32 s1, s48, 6
	s_add_u32 s1, s0, s1
	s_cmpk_gt_i32 s1, 0xd7f
	s_cbranch_scc1 .Lp0t_st_end
	s_cmpk_lt_u32 s1, 0x580
	s_cbranch_scc0 .Lp0t_st_14_n0
	s_mov_b32 s2, s1
	s_mul_hi_u32 s3, s2, 0x2e8ba2e9
	s_lshr_b32 s3, s3, 4
	s_mul_i32 s4, s3, 88
	s_sub_u32 s4, s2, s4
	s_mul_i32 s5, s4, 0x20000
	s_lshl_b32 s6, s3, 7
	s_add_u32 s5, s5, s6
	s_add_u32 s14, s90, s5
	s_addc_u32 s15, s91, 0
	s_mov_b32 s16, 0x800
	s_branch .Lp0t_st_14_done

.Lp0t_st_14_done:
	v_add_u32_e32 v9, 0x18600, v6
	v_add_u32_e32 v12, 0x400, v9
	ds_read2_b32 v[14:15], v9 offset1:65
	ds_read2_b32 v[16:17], v9 offset0:130 offset1:195
	ds_read2_b32 v[18:19], v12 offset0:4 offset1:69
	ds_read2_b32 v[20:21], v12 offset0:134 offset1:199
	v_mad_u32_u24 v13, v4, s16, v7
	s_waitcnt lgkmcnt(0)
	v_cvt_pk_bf16_f32 v22, v14, v15
	v_cvt_pk_bf16_f32 v23, v16, v17
	v_cvt_pk_bf16_f32 v24, v18, v19
	v_cvt_pk_bf16_f32 v25, v20, v21
	global_store_dwordx4 v13, v[22:25], s[14:15]
.Lp0t_st_end:
	s_barrier
	s_mul_i32 s1, s48, 7
	s_add_u32 s0, s0, s1
	s_branch .Lp0t_batch
